# attention loop: first V-fragment LDS reads issued before the row-max block so their latency overlaps it
# speedup vs baseline: 1.0140x; 1.0131x over previous
.LBB0_861:
	ds_read_b64_tr_b16 v[148:149], v215 offset:17408
	ds_read_b64_tr_b16 v[152:153], v215 offset:17440
	ds_read_b64_tr_b16 v[156:157], v215 offset:17472
	ds_read_b64_tr_b16 v[160:161], v215 offset:17504
	ds_read_b64_tr_b16 v[150:151], v215 offset:22016
	ds_read_b64_tr_b16 v[154:155], v215 offset:22048
	ds_read_b64_tr_b16 v[158:159], v215 offset:22080
	ds_read_b64_tr_b16 v[162:163], v215 offset:22112
	v_max_f32_e32 v0, v144, v145
	v_max3_f32 v2, v147, v44, v45
	v_max3_f32 v0, v0, v146, v46
	v_max3_f32 v2, v2, v140, v141
	v_max3_f32 v0, v0, v47, v142
	v_max3_f32 v2, v2, v72, v73
	v_max3_f32 v0, v0, v143, v74
	v_max3_f32 v0, v0, v75, v2
	v_max_f32_e32 v2, v136, v137
	v_max3_f32 v3, v139, v92, v93
	v_max3_f32 v2, v2, v138, v94
	v_max3_f32 v3, v3, v132, v133
	v_max3_f32 v2, v2, v95, v134
	v_max3_f32 v3, v3, v112, v113
	v_max3_f32 v2, v2, v135, v114
	v_max3_f32 v2, v2, v115, v3
	v_max_f32_e32 v3, v0, v2
	v_cmp_lt_f32_e32 vcc, s74, v3
	s_cmp_lg_u64 vcc, 0
	s_cselect_b64 s[0:1], -1, 0
	s_cbranch_vccz .LBB0_863
	s_waitcnt lgkmcnt(0)
	s_mov_b32 s98, 1
	v_and_b32_e32 v148, 64, v212
	v_xor_b32_e32 v3, 16, v212
	v_add_u32_e32 v148, 64, v148
	v_cmp_lt_i32_e32 vcc, v3, v148
	v_xor_b32_e32 v149, 32, v212
	s_nop 0
	v_cndmask_b32_e32 v3, v212, v3, vcc
	v_lshlrev_b32_e32 v3, 2, v3
	ds_bpermute_b32 v150, v3, v0
	ds_bpermute_b32 v3, v3, v2
	v_cmp_lt_i32_e32 vcc, v149, v148
	v_max_f32_e32 v2, v2, v2
	v_max_f32_e32 v0, v0, v0
	v_cndmask_b32_e32 v148, v212, v149, vcc
	s_waitcnt lgkmcnt(0)
	v_max_f32_e32 v3, v3, v3
	v_lshlrev_b32_e32 v148, 2, v148
	v_max_f32_e32 v149, v150, v150
	v_max_f32_e32 v2, v2, v3
	v_max_f32_e32 v0, v0, v149
	ds_bpermute_b32 v3, v148, v2
	ds_bpermute_b32 v149, v148, v0
	s_waitcnt lgkmcnt(1)
	v_max_f32_e32 v3, v3, v3
	s_waitcnt lgkmcnt(0)
	v_max_f32_e32 v148, v149, v149
	v_max_f32_e32 v2, v2, v3
	v_max_f32_e32 v0, v0, v148
	v_cmp_lt_f32_e32 vcc, s74, v2
	s_nop 1
	v_cndmask_b32_e32 v3, 0, v2, vcc
	v_cmp_lt_f32_e32 vcc, s74, v0
	v_exp_f32_e64 v201, -v3
	v_sub_f32_e32 v136, v136, v3
	v_cndmask_b32_e32 v2, 0, v0, vcc
	v_exp_f32_e64 v200, -v2
	v_sub_f32_e32 v144, v144, v2
	v_sub_f32_e32 v145, v145, v2
	v_sub_f32_e32 v146, v146, v2
	v_sub_f32_e32 v147, v147, v2
	v_sub_f32_e32 v44, v44, v2
	v_sub_f32_e32 v45, v45, v2
	v_sub_f32_e32 v46, v46, v2
	v_sub_f32_e32 v47, v47, v2
	v_sub_f32_e32 v140, v140, v2
	v_sub_f32_e32 v141, v141, v2
	v_sub_f32_e32 v142, v142, v2
	v_sub_f32_e32 v143, v143, v2
	v_sub_f32_e32 v72, v72, v2
	v_sub_f32_e32 v73, v73, v2
	v_sub_f32_e32 v74, v74, v2
	v_sub_f32_e32 v75, v75, v2
	v_pk_add_f32 v[196:197], v[196:197], v[2:3]
	v_sub_f32_e32 v137, v137, v3
	v_sub_f32_e32 v138, v138, v3
	v_sub_f32_e32 v139, v139, v3
	v_sub_f32_e32 v92, v92, v3
	v_sub_f32_e32 v93, v93, v3
	v_sub_f32_e32 v94, v94, v3
	v_sub_f32_e32 v95, v95, v3
	v_sub_f32_e32 v132, v132, v3
	v_sub_f32_e32 v133, v133, v3
	v_sub_f32_e32 v134, v134, v3
	v_sub_f32_e32 v135, v135, v3
	v_sub_f32_e32 v112, v112, v3
	v_sub_f32_e32 v113, v113, v3
	v_sub_f32_e32 v114, v114, v3
	v_sub_f32_e32 v115, v115, v3
	v_pk_mul_f32 v[198:199], v[198:199], v[200:201]
	ds_read_b64_tr_b16 v[148:149], v215 offset:17408
	ds_read_b64_tr_b16 v[152:153], v215 offset:17440
	ds_read_b64_tr_b16 v[156:157], v215 offset:17472
	ds_read_b64_tr_b16 v[160:161], v215 offset:17504
	ds_read_b64_tr_b16 v[150:151], v215 offset:22016
	ds_read_b64_tr_b16 v[154:155], v215 offset:22048
	ds_read_b64_tr_b16 v[158:159], v215 offset:22080
	ds_read_b64_tr_b16 v[162:163], v215 offset:22112
.LBB0_863:
	v_exp_f32_e32 v2, v144
	s_waitcnt lgkmcnt(3)
	v_mfma_f32_16x16x32_bf16 v[164:167], v[36:39], v[148:151], v[128:131]
	v_exp_f32_e32 v222, v145
	v_mfma_f32_16x16x32_bf16 v[148:151], v[60:63], v[148:151], v[120:123]
	ds_read_b64_tr_b16 v[238:239], v215 offset:17536
	ds_read_b64_tr_b16 v[242:243], v215 offset:17568
	ds_read_b64_tr_b16 v[246:247], v215 offset:17600
	ds_read_b64_tr_b16 v[250:251], v215 offset:17632
	ds_read_b64_tr_b16 v[240:241], v215 offset:22144
	ds_read_b64_tr_b16 v[244:245], v215 offset:22176
	ds_read_b64_tr_b16 v[248:249], v215 offset:22208
	ds_read_b64_tr_b16 v[252:253], v215 offset:22240
	v_exp_f32_e32 v224, v146
	s_waitcnt lgkmcnt(8)
	v_mfma_f32_16x16x32_bf16 v[124:127], v[36:39], v[152:155], v[124:127]
	v_exp_f32_e32 v122, v147
	v_mfma_f32_16x16x32_bf16 v[152:155], v[60:63], v[152:155], v[108:111]
	v_exp_f32_e32 v226, v44
	v_mfma_f32_16x16x32_bf16 v[116:119], v[36:39], v[156:159], v[116:119]
	v_exp_f32_e32 v110, v45
	v_mfma_f32_16x16x32_bf16 v[168:171], v[60:63], v[156:159], v[100:103]
	v_exp_f32_e32 v228, v46
	v_mfma_f32_16x16x32_bf16 v[104:107], v[36:39], v[160:163], v[104:107]
	v_exp_f32_e32 v100, v47
	v_mfma_f32_16x16x32_bf16 v[160:163], v[60:63], v[160:163], v[96:99]
	v_cvt_pk_bf16_f32 v44, v2, v222
	v_cvt_pk_bf16_f32 v45, v224, v122
	v_cvt_pk_bf16_f32 v46, v226, v110
	v_cvt_pk_bf16_f32 v47, v228, v100
	v_exp_f32_e32 v96, v140
	s_waitcnt lgkmcnt(0)
	v_mfma_f32_16x16x32_bf16 v[180:183], v[36:39], v[238:241], v[88:91]
	v_exp_f32_e32 v230, v141
	v_mfma_f32_16x16x32_bf16 v[184:187], v[60:63], v[238:241], v[76:79]
	v_exp_f32_e32 v232, v142
	v_mfma_f32_16x16x32_bf16 v[80:83], v[36:39], v[242:245], v[80:83]
	v_exp_f32_e32 v78, v143
	v_mfma_f32_16x16x32_bf16 v[188:191], v[60:63], v[242:245], v[64:67]
	ds_read_b64_tr_b16 v[140:141], v215 offset:26624
	ds_read_b64_tr_b16 v[156:157], v215 offset:26656
	ds_read_b64_tr_b16 v[172:173], v215 offset:26688
	ds_read_b64_tr_b16 v[176:177], v215 offset:26720
	ds_read_b64_tr_b16 v[142:143], v215 offset:31232
	ds_read_b64_tr_b16 v[158:159], v215 offset:31264
	ds_read_b64_tr_b16 v[174:175], v215 offset:31296
	ds_read_b64_tr_b16 v[178:179], v215 offset:31328
	v_exp_f32_e32 v234, v72
	v_mfma_f32_16x16x32_bf16 v[68:71], v[36:39], v[246:249], v[68:71]
	v_exp_f32_e32 v66, v73
	v_mfma_f32_16x16x32_bf16 v[192:195], v[60:63], v[246:249], v[52:55]
	v_exp_f32_e32 v236, v74
	v_mfma_f32_16x16x32_bf16 v[56:59], v[36:39], v[250:253], v[56:59]
	v_exp_f32_e32 v54, v75
	v_mfma_f32_16x16x32_bf16 v[48:51], v[60:63], v[250:253], v[48:51]
	v_cvt_pk_bf16_f32 v72, v96, v230
	v_cvt_pk_bf16_f32 v73, v232, v78
	v_cvt_pk_bf16_f32 v74, v234, v66
	v_cvt_pk_bf16_f32 v75, v236, v54
	v_exp_f32_e32 v3, v136
	s_waitcnt lgkmcnt(0)
	v_mfma_f32_16x16x32_bf16 v[144:147], v[40:43], v[140:143], v[164:167]
	v_exp_f32_e32 v223, v137
	v_mfma_f32_16x16x32_bf16 v[140:143], v[84:87], v[140:143], v[148:151]
	ds_read_b64_tr_b16 v[238:239], v215 offset:26752
	ds_read_b64_tr_b16 v[242:243], v215 offset:26784
	ds_read_b64_tr_b16 v[246:247], v215 offset:26816
	ds_read_b64_tr_b16 v[250:251], v215 offset:26848
	ds_read_b64_tr_b16 v[240:241], v215 offset:31360
	ds_read_b64_tr_b16 v[244:245], v215 offset:31392
	ds_read_b64_tr_b16 v[248:249], v215 offset:31424
	ds_read_b64_tr_b16 v[252:253], v215 offset:31456
	v_exp_f32_e32 v225, v138
	v_mfma_f32_16x16x32_bf16 v[148:151], v[40:43], v[156:159], v[124:127]
	v_exp_f32_e32 v123, v139
	v_mfma_f32_16x16x32_bf16 v[136:139], v[84:87], v[156:159], v[152:155]
	v_exp_f32_e32 v227, v92
	v_mfma_f32_16x16x32_bf16 v[156:159], v[40:43], v[172:175], v[116:119]
	v_exp_f32_e32 v111, v93
	v_mfma_f32_16x16x32_bf16 v[152:155], v[84:87], v[172:175], v[168:171]
	v_exp_f32_e32 v229, v94
	v_mfma_f32_16x16x32_bf16 v[164:167], v[40:43], v[176:179], v[104:107]
	v_exp_f32_e32 v101, v95
	v_mfma_f32_16x16x32_bf16 v[160:163], v[84:87], v[176:179], v[160:163]
	s_nop 0
	v_cvt_pk_bf16_f32 v92, v3, v223
	v_cvt_pk_bf16_f32 v93, v225, v123
	v_cvt_pk_bf16_f32 v94, v227, v111
	v_cvt_pk_bf16_f32 v95, v229, v101
	v_exp_f32_e32 v97, v132
	s_waitcnt lgkmcnt(0)
	v_mfma_f32_16x16x32_bf16 v[172:175], v[40:43], v[238:241], v[180:183]
	v_exp_f32_e32 v231, v133
	v_mfma_f32_16x16x32_bf16 v[168:171], v[84:87], v[238:241], v[184:187]
	v_exp_f32_e32 v233, v134
	v_mfma_f32_16x16x32_bf16 v[176:179], v[40:43], v[242:245], v[80:83]
	v_exp_f32_e32 v79, v135
	v_mfma_f32_16x16x32_bf16 v[132:135], v[84:87], v[242:245], v[188:191]
	v_exp_f32_e32 v235, v112
	v_mfma_f32_16x16x32_bf16 v[184:187], v[40:43], v[246:249], v[68:71]
	v_exp_f32_e32 v67, v113
	v_mfma_f32_16x16x32_bf16 v[180:183], v[84:87], v[246:249], v[192:195]
	v_exp_f32_e32 v237, v114
	v_mfma_f32_16x16x32_bf16 v[192:195], v[40:43], v[250:253], v[56:59]
	v_exp_f32_e32 v55, v115
	v_mfma_f32_16x16x32_bf16 v[188:191], v[84:87], v[250:253], v[48:51]
	s_andn2_b64 vcc, exec, s[0:1]
	s_cbranch_vccnz .LBB0_865
	v_mov_b32_e32 v0, v210
	s_nop 0
	v_lshlrev_b32_e32 v0, 2, v0
	v_and_b32_e32 v0, 60, v0
	v_and_or_b32 v0, v212, 64, v0
	v_lshlrev_b32_e32 v0, 2, v0
	ds_bpermute_b32 v48, v0, v200
	ds_bpermute_b32 v50, v0, v200 offset:8
	ds_bpermute_b32 v51, v0, v200 offset:12
	ds_bpermute_b32 v49, v0, v200 offset:4
	ds_bpermute_b32 v56, v0, v201
	ds_bpermute_b32 v58, v0, v201 offset:8
	ds_bpermute_b32 v59, v0, v201 offset:12
	ds_bpermute_b32 v57, v0, v201 offset:4
	s_waitcnt lgkmcnt(5)
	v_pk_mul_f32 v[146:147], v[146:147], v[50:51]
	s_waitcnt lgkmcnt(4)
	v_pk_mul_f32 v[144:145], v[144:145], v[48:49]
	v_pk_mul_f32 v[150:151], v[150:151], v[50:51]
	v_pk_mul_f32 v[148:149], v[148:149], v[48:49]
	v_pk_mul_f32 v[158:159], v[158:159], v[50:51]
	v_pk_mul_f32 v[156:157], v[156:157], v[48:49]
	v_pk_mul_f32 v[166:167], v[166:167], v[50:51]
	v_pk_mul_f32 v[164:165], v[164:165], v[48:49]
	v_pk_mul_f32 v[174:175], v[174:175], v[50:51]
	v_pk_mul_f32 v[172:173], v[172:173], v[48:49]
	v_pk_mul_f32 v[178:179], v[178:179], v[50:51]
	v_pk_mul_f32 v[176:177], v[176:177], v[48:49]
	v_pk_mul_f32 v[186:187], v[186:187], v[50:51]
	v_pk_mul_f32 v[184:185], v[184:185], v[48:49]
	v_pk_mul_f32 v[194:195], v[194:195], v[50:51]
	v_pk_mul_f32 v[192:193], v[192:193], v[48:49]
	s_waitcnt lgkmcnt(1)
	v_pk_mul_f32 v[142:143], v[142:143], v[58:59]
	s_waitcnt lgkmcnt(0)
	v_pk_mul_f32 v[140:141], v[140:141], v[56:57]
	v_pk_mul_f32 v[138:139], v[138:139], v[58:59]
	v_pk_mul_f32 v[136:137], v[136:137], v[56:57]
	v_pk_mul_f32 v[154:155], v[154:155], v[58:59]
	v_pk_mul_f32 v[152:153], v[152:153], v[56:57]
	v_pk_mul_f32 v[162:163], v[162:163], v[58:59]
	v_pk_mul_f32 v[160:161], v[160:161], v[56:57]
	v_pk_mul_f32 v[170:171], v[170:171], v[58:59]
	v_pk_mul_f32 v[168:169], v[168:169], v[56:57]
	v_pk_mul_f32 v[134:135], v[134:135], v[58:59]
	v_pk_mul_f32 v[132:133], v[132:133], v[56:57]
	v_pk_mul_f32 v[182:183], v[182:183], v[58:59]
	v_pk_mul_f32 v[180:181], v[180:181], v[56:57]
	v_pk_mul_f32 v[190:191], v[190:191], v[58:59]
	v_pk_mul_f32 v[188:189], v[188:189], v[56:57]

.LBB0_877:
	ds_read_b64_tr_b16 v[124:125], v215 offset:53248
	ds_read_b64_tr_b16 v[100:101], v215 offset:53280
	ds_read_b64_tr_b16 v[116:117], v215 offset:53312
	ds_read_b64_tr_b16 v[96:97], v215 offset:53344
	ds_read_b64_tr_b16 v[126:127], v215 offset:57856
	ds_read_b64_tr_b16 v[102:103], v215 offset:57888
	ds_read_b64_tr_b16 v[118:119], v215 offset:57920
	ds_read_b64_tr_b16 v[98:99], v215 offset:57952
	v_max_f32_e32 v0, v128, v129
	v_max3_f32 v2, v131, v36, v37
	v_max3_f32 v0, v0, v130, v38
	v_max3_f32 v2, v2, v120, v121
	v_max3_f32 v0, v0, v39, v122
	v_max3_f32 v2, v2, v40, v41
	v_max3_f32 v0, v0, v123, v42
	v_max3_f32 v0, v0, v43, v2
	v_max_f32_e32 v2, v108, v109
	v_max3_f32 v3, v111, v60, v61
	v_max3_f32 v2, v2, v110, v62
	v_max3_f32 v3, v3, v64, v65
	v_max3_f32 v2, v2, v63, v66
	v_max3_f32 v3, v3, v84, v85
	v_max3_f32 v2, v2, v67, v86
	v_max3_f32 v2, v2, v87, v3
	v_max_f32_e32 v3, v0, v2
	v_cmp_lt_f32_e32 vcc, s74, v3
	s_cmp_lg_u64 vcc, 0
	s_cselect_b64 s[2:3], -1, 0
	s_cbranch_vccz .LBB0_879
	s_waitcnt lgkmcnt(0)
	s_mov_b32 s98, 1
	v_and_b32_e32 v124, 64, v212
	v_xor_b32_e32 v3, 16, v212
	v_add_u32_e32 v124, 64, v124
	v_cmp_lt_i32_e32 vcc, v3, v124
	v_xor_b32_e32 v125, 32, v212
	s_nop 0
	v_cndmask_b32_e32 v3, v212, v3, vcc
	v_lshlrev_b32_e32 v3, 2, v3
	ds_bpermute_b32 v126, v3, v0
	ds_bpermute_b32 v3, v3, v2
	v_cmp_lt_i32_e32 vcc, v125, v124
	v_max_f32_e32 v2, v2, v2
	v_max_f32_e32 v0, v0, v0
	v_cndmask_b32_e32 v124, v212, v125, vcc
	s_waitcnt lgkmcnt(0)
	v_max_f32_e32 v3, v3, v3
	v_lshlrev_b32_e32 v124, 2, v124
	v_max_f32_e32 v125, v126, v126
	v_max_f32_e32 v2, v2, v3
	v_max_f32_e32 v0, v0, v125
	ds_bpermute_b32 v3, v124, v2
	ds_bpermute_b32 v125, v124, v0
	s_waitcnt lgkmcnt(1)
	v_max_f32_e32 v3, v3, v3
	s_waitcnt lgkmcnt(0)
	v_max_f32_e32 v124, v125, v125
	v_max_f32_e32 v2, v2, v3
	v_max_f32_e32 v0, v0, v124
	v_cmp_lt_f32_e32 vcc, s74, v2
	s_nop 1
	v_cndmask_b32_e32 v3, 0, v2, vcc
	v_cmp_lt_f32_e32 vcc, s74, v0
	v_exp_f32_e64 v201, -v3
	v_sub_f32_e32 v108, v108, v3
	v_cndmask_b32_e32 v2, 0, v0, vcc
	v_exp_f32_e64 v200, -v2
	v_sub_f32_e32 v128, v128, v2
	v_sub_f32_e32 v129, v129, v2
	v_sub_f32_e32 v130, v130, v2
	v_sub_f32_e32 v131, v131, v2
	v_sub_f32_e32 v36, v36, v2
	v_sub_f32_e32 v37, v37, v2
	v_sub_f32_e32 v38, v38, v2
	v_sub_f32_e32 v39, v39, v2
	v_sub_f32_e32 v120, v120, v2
	v_sub_f32_e32 v121, v121, v2
	v_sub_f32_e32 v122, v122, v2
	v_sub_f32_e32 v123, v123, v2
	v_sub_f32_e32 v40, v40, v2
	v_sub_f32_e32 v41, v41, v2
	v_sub_f32_e32 v42, v42, v2
	v_sub_f32_e32 v43, v43, v2
	v_pk_add_f32 v[196:197], v[196:197], v[2:3]
	v_sub_f32_e32 v109, v109, v3
	v_sub_f32_e32 v110, v110, v3
	v_sub_f32_e32 v111, v111, v3
	v_sub_f32_e32 v60, v60, v3
	v_sub_f32_e32 v61, v61, v3
	v_sub_f32_e32 v62, v62, v3
	v_sub_f32_e32 v63, v63, v3
	v_sub_f32_e32 v64, v64, v3
	v_sub_f32_e32 v65, v65, v3
	v_sub_f32_e32 v66, v66, v3
	v_sub_f32_e32 v67, v67, v3
	v_sub_f32_e32 v84, v84, v3
	v_sub_f32_e32 v85, v85, v3
	v_sub_f32_e32 v86, v86, v3
	v_sub_f32_e32 v87, v87, v3
	v_pk_mul_f32 v[198:199], v[198:199], v[200:201]
	ds_read_b64_tr_b16 v[124:125], v215 offset:53248
	ds_read_b64_tr_b16 v[100:101], v215 offset:53280
	ds_read_b64_tr_b16 v[116:117], v215 offset:53312
	ds_read_b64_tr_b16 v[96:97], v215 offset:53344
	ds_read_b64_tr_b16 v[126:127], v215 offset:57856
	ds_read_b64_tr_b16 v[102:103], v215 offset:57888
	ds_read_b64_tr_b16 v[118:119], v215 offset:57920
	ds_read_b64_tr_b16 v[98:99], v215 offset:57952
.LBB0_879:
	v_exp_f32_e32 v2, v128
	s_waitcnt lgkmcnt(3)
	v_mfma_f32_16x16x32_bf16 v[104:107], v[44:47], v[124:127], v[144:147]
	v_exp_f32_e32 v222, v129
	v_mfma_f32_16x16x32_bf16 v[124:127], v[92:95], v[124:127], v[140:143]
	ds_read_b64_tr_b16 v[238:239], v215 offset:53376
	ds_read_b64_tr_b16 v[242:243], v215 offset:53408
	ds_read_b64_tr_b16 v[246:247], v215 offset:53440
	ds_read_b64_tr_b16 v[250:251], v215 offset:53472
	ds_read_b64_tr_b16 v[240:241], v215 offset:57984
	ds_read_b64_tr_b16 v[244:245], v215 offset:58016
	ds_read_b64_tr_b16 v[248:249], v215 offset:58048
	ds_read_b64_tr_b16 v[252:253], v215 offset:58080
	v_exp_f32_e32 v224, v130
	s_waitcnt lgkmcnt(8)
	v_mfma_f32_16x16x32_bf16 v[148:151], v[44:47], v[100:103], v[148:151]
	v_exp_f32_e32 v142, v131
	v_mfma_f32_16x16x32_bf16 v[100:103], v[92:95], v[100:103], v[136:139]
	v_exp_f32_e32 v226, v36
	v_mfma_f32_16x16x32_bf16 v[156:159], v[44:47], v[116:119], v[156:159]
	v_exp_f32_e32 v138, v37
	v_mfma_f32_16x16x32_bf16 v[76:79], v[92:95], v[116:119], v[152:155]
	v_exp_f32_e32 v228, v38
	v_mfma_f32_16x16x32_bf16 v[164:167], v[44:47], v[96:99], v[164:167]
	v_exp_f32_e32 v154, v39
	v_mfma_f32_16x16x32_bf16 v[96:99], v[92:95], v[96:99], v[160:163]
	v_cvt_pk_bf16_f32 v36, v2, v222
	v_cvt_pk_bf16_f32 v37, v224, v142
	v_cvt_pk_bf16_f32 v38, v226, v138
	v_cvt_pk_bf16_f32 v39, v228, v154
	v_exp_f32_e32 v160, v120
	s_waitcnt lgkmcnt(0)
	v_mfma_f32_16x16x32_bf16 v[52:55], v[44:47], v[238:241], v[172:175]
	v_exp_f32_e32 v230, v121
	v_mfma_f32_16x16x32_bf16 v[68:71], v[92:95], v[238:241], v[168:171]
	v_exp_f32_e32 v232, v122
	v_mfma_f32_16x16x32_bf16 v[176:179], v[44:47], v[242:245], v[176:179]
	v_exp_f32_e32 v170, v123
	v_mfma_f32_16x16x32_bf16 v[48:51], v[92:95], v[242:245], v[132:135]
	ds_read_b64_tr_b16 v[120:121], v215 offset:62464
	ds_read_b64_tr_b16 v[116:117], v215 offset:62496
	ds_read_b64_tr_b16 v[88:89], v215 offset:62528
	ds_read_b64_tr_b16 v[80:81], v215 offset:62560
	ds_read_b64_tr_b16 v[122:123], v216 offset:13824
	ds_read_b64_tr_b16 v[118:119], v216 offset:13856
	ds_read_b64_tr_b16 v[90:91], v216 offset:13888
	ds_read_b64_tr_b16 v[82:83], v216 offset:13920
	v_exp_f32_e32 v234, v40
	v_mfma_f32_16x16x32_bf16 v[184:187], v[44:47], v[246:249], v[184:187]
	v_exp_f32_e32 v134, v41
	v_mfma_f32_16x16x32_bf16 v[56:59], v[92:95], v[246:249], v[180:183]
	v_exp_f32_e32 v236, v42
	v_mfma_f32_16x16x32_bf16 v[192:195], v[44:47], v[250:253], v[192:195]
	v_exp_f32_e32 v182, v43
	v_mfma_f32_16x16x32_bf16 v[188:191], v[92:95], v[250:253], v[188:191]
	v_cvt_pk_bf16_f32 v40, v160, v230
	v_cvt_pk_bf16_f32 v41, v232, v170
	v_cvt_pk_bf16_f32 v42, v234, v134
	v_cvt_pk_bf16_f32 v43, v236, v182
	v_exp_f32_e32 v3, v108
	s_waitcnt lgkmcnt(0)
	v_mfma_f32_16x16x32_bf16 v[128:131], v[72:75], v[120:123], v[104:107]
	v_exp_f32_e32 v223, v109
	v_mfma_f32_16x16x32_bf16 v[120:123], v[112:115], v[120:123], v[124:127]
	ds_read_b64_tr_b16 v[238:239], v215 offset:62592
	ds_read_b64_tr_b16 v[242:243], v215 offset:62624
	ds_read_b64_tr_b16 v[246:247], v215 offset:62656
	ds_read_b64_tr_b16 v[250:251], v215 offset:62688
	ds_read_b64_tr_b16 v[240:241], v216 offset:13952
	ds_read_b64_tr_b16 v[244:245], v216 offset:13984
	ds_read_b64_tr_b16 v[248:249], v216 offset:14016
	ds_read_b64_tr_b16 v[252:253], v216 offset:14048
	v_exp_f32_e32 v225, v110
	v_mfma_f32_16x16x32_bf16 v[124:127], v[72:75], v[116:119], v[148:151]
	v_exp_f32_e32 v143, v111
	v_mfma_f32_16x16x32_bf16 v[108:111], v[112:115], v[116:119], v[100:103]
	v_exp_f32_e32 v227, v60
	v_mfma_f32_16x16x32_bf16 v[116:119], v[72:75], v[88:91], v[156:159]
	v_exp_f32_e32 v139, v61
	v_mfma_f32_16x16x32_bf16 v[100:103], v[112:115], v[88:91], v[76:79]
	v_exp_f32_e32 v229, v62
	v_mfma_f32_16x16x32_bf16 v[104:107], v[72:75], v[80:83], v[164:167]
	v_exp_f32_e32 v155, v63
	v_mfma_f32_16x16x32_bf16 v[96:99], v[112:115], v[80:83], v[96:99]
	s_nop 0
	v_cvt_pk_bf16_f32 v60, v3, v223
	v_cvt_pk_bf16_f32 v61, v225, v143
	v_cvt_pk_bf16_f32 v62, v227, v139
	v_cvt_pk_bf16_f32 v63, v229, v155
	v_exp_f32_e32 v161, v64
	s_waitcnt lgkmcnt(0)
	v_mfma_f32_16x16x32_bf16 v[88:91], v[72:75], v[238:241], v[52:55]
	v_exp_f32_e32 v231, v65
	v_mfma_f32_16x16x32_bf16 v[76:79], v[112:115], v[238:241], v[68:71]
	v_exp_f32_e32 v233, v66
	v_mfma_f32_16x16x32_bf16 v[80:83], v[72:75], v[242:245], v[176:179]
	v_exp_f32_e32 v171, v67
	v_mfma_f32_16x16x32_bf16 v[64:67], v[112:115], v[242:245], v[48:51]
	v_exp_f32_e32 v235, v84
	v_mfma_f32_16x16x32_bf16 v[68:71], v[72:75], v[246:249], v[184:187]
	v_exp_f32_e32 v135, v85
	v_mfma_f32_16x16x32_bf16 v[52:55], v[112:115], v[246:249], v[56:59]
	v_exp_f32_e32 v237, v86
	v_mfma_f32_16x16x32_bf16 v[56:59], v[72:75], v[250:253], v[192:195]
	v_exp_f32_e32 v183, v87
	v_mfma_f32_16x16x32_bf16 v[48:51], v[112:115], v[250:253], v[188:191]
	s_andn2_b64 vcc, exec, s[2:3]
	s_cbranch_vccnz .LBB0_881
	v_mov_b32_e32 v0, v210
	s_nop 0
	v_lshlrev_b32_e32 v0, 2, v0
	v_and_b32_e32 v0, 60, v0
	v_and_or_b32 v0, v212, 64, v0
	v_lshlrev_b32_e32 v0, 2, v0
	ds_bpermute_b32 v188, v0, v200
	ds_bpermute_b32 v190, v0, v200 offset:8
	ds_bpermute_b32 v191, v0, v200 offset:12
	ds_bpermute_b32 v189, v0, v200 offset:4
	ds_bpermute_b32 v192, v0, v201
	ds_bpermute_b32 v194, v0, v201 offset:8
	ds_bpermute_b32 v195, v0, v201 offset:12
	ds_bpermute_b32 v193, v0, v201 offset:4
	s_waitcnt lgkmcnt(5)
	v_pk_mul_f32 v[130:131], v[130:131], v[190:191]
	s_waitcnt lgkmcnt(4)
	v_pk_mul_f32 v[128:129], v[128:129], v[188:189]
	v_pk_mul_f32 v[126:127], v[126:127], v[190:191]
	v_pk_mul_f32 v[124:125], v[124:125], v[188:189]
	v_pk_mul_f32 v[118:119], v[118:119], v[190:191]
	v_pk_mul_f32 v[116:117], v[116:117], v[188:189]
	v_pk_mul_f32 v[106:107], v[106:107], v[190:191]
	v_pk_mul_f32 v[104:105], v[104:105], v[188:189]
	v_pk_mul_f32 v[90:91], v[90:91], v[190:191]
	v_pk_mul_f32 v[88:89], v[88:89], v[188:189]
	v_pk_mul_f32 v[82:83], v[82:83], v[190:191]
	v_pk_mul_f32 v[80:81], v[80:81], v[188:189]
	v_pk_mul_f32 v[70:71], v[70:71], v[190:191]
	v_pk_mul_f32 v[68:69], v[68:69], v[188:189]
	v_pk_mul_f32 v[58:59], v[58:59], v[190:191]
	v_pk_mul_f32 v[56:57], v[56:57], v[188:189]
	s_waitcnt lgkmcnt(1)
	v_pk_mul_f32 v[122:123], v[122:123], v[194:195]
	s_waitcnt lgkmcnt(0)
	v_pk_mul_f32 v[120:121], v[120:121], v[192:193]
	v_pk_mul_f32 v[110:111], v[110:111], v[194:195]
	v_pk_mul_f32 v[108:109], v[108:109], v[192:193]
	v_pk_mul_f32 v[102:103], v[102:103], v[194:195]
	v_pk_mul_f32 v[100:101], v[100:101], v[192:193]
	v_pk_mul_f32 v[98:99], v[98:99], v[194:195]
	v_pk_mul_f32 v[96:97], v[96:97], v[192:193]
	v_pk_mul_f32 v[78:79], v[78:79], v[194:195]
	v_pk_mul_f32 v[76:77], v[76:77], v[192:193]
	v_pk_mul_f32 v[66:67], v[66:67], v[194:195]
	v_pk_mul_f32 v[64:65], v[64:65], v[192:193]
	v_pk_mul_f32 v[54:55], v[54:55], v[194:195]
	v_pk_mul_f32 v[52:53], v[52:53], v[192:193]
	v_pk_mul_f32 v[50:51], v[50:51], v[194:195]
	v_pk_mul_f32 v[48:49], v[48:49], v[192:193]
